# same as previous plus one counted wait bounding outstanding stores in the mode-1 output section
# speedup vs baseline: 1.0018x; 1.0018x over previous
; #define LAS __attribute__((address_space(3)))
; template <int MODE> __device__ __forceinline__ void rwkv_item(const Params& P, int e, int c, int h, LAS float* slab, int lane) {
;     ...
;         for (int s = 0; s < SB; ++s) {
;             const LAS float* st = slab + s * 512;
;             f32x2 aS0 = {0.f, 0.f}, aS1 = {0.f, 0.f}, aC0 = {0.f, 0.f}, aC1 = {0.f, 0.f};
;             constexpr int DB = 4, UB = 2;
;             constexpr int NDB = 16 / DB, NUB = 16 / UB;
;             constexpr int NB = MODE == 1 ? 2 : 1;
;             f32x4 kd[NB][DB];
;             f32x4 wq[NB][UB], bq[NB][UB], kq[NB][UB], rq[NB][MODE == 1 ? UB : 1];
;     ...
;             if (NB == 2) RW_LD_DOT(0, 0);
;             const float v = st[320 + lane];
; #pragma unroll
;             for (int hb = 0; hb < NDB; ++hb) {
;                 if (NB == 2) { if (hb + 1 < NDB) RW_LD_DOT((hb + 1) & 1, hb + 1); else RW_LD_UPD(0, 0); } else RW_LD_DOT(0, hb);
;                 __builtin_amdgcn_sched_barrier(0);
; #pragma unroll
;                 for (int q = 0; q < DB; ++q) {
;                     const int qq = DB * hb + q; const f32x4 k4 = kd[hb & (NB - 1)][q];
;                     aS0 += S2[2 * qq] * (f32x2){k4.x, k4.y}; aS1 += S2[2 * qq + 1] * (f32x2){k4.z, k4.w};
;                     if (MODE == 0) { aC0 += C2[2 * qq] * (f32x2){k4.x, k4.y}; aC1 += C2[2 * qq + 1] * (f32x2){k4.z, k4.w}; }
;                 }
;                 __builtin_amdgcn_sched_barrier(0);
;             }
;             const float nsk = -((aS0.x + aS0.y) + (aS1.x + aS1.y));
;             const float nskC = -((aC0.x + aC0.y) + (aC1.x + aC1.y));
;             f32x2 y0 = {0.f, 0.f}, y1 = {0.f, 0.f};
; #pragma unroll
;             for (int qb = 0; qb < NUB; ++qb) {
;                 if (NB == 2) { if (qb + 1 < NUB) RW_LD_UPD((qb + 1) & 1, qb + 1); } else RW_LD_UPD(0, qb);
;                 __builtin_amdgcn_sched_barrier(0);
; #pragma unroll
;                 for (int q = 0; q < UB; ++q) {
;                     const int qq = UB * qb + q;
;                     const f32x4 w4 = wq[qb & (NB - 1)][q], b4 = bq[qb & (NB - 1)][q], k4 = kq[qb & (NB - 1)][q];
;                     if (MODE == 0) {
;                         S2[2 * qq] = S2[2 * qq] * (f32x2){w4.x, w4.y} + (f32x2){b4.x, b4.y} * nsk;
;                         S2[2 * qq + 1] = S2[2 * qq + 1] * (f32x2){w4.z, w4.w} + (f32x2){b4.z, b4.w} * nsk;
.Lm1_step:
	s_add_i32 s8, s3, s11
	v_add_u32_e32 v197, s11, v109
	v_mov_b32_e32 v196, s8
	ds_read_b32 v194, v197 offset:1280
	ds_read_b128 v[136:139], v196 offset:256
	ds_read_b128 v[140:143], v196 offset:272
	ds_read_b128 v[144:147], v196 offset:288
	ds_read_b128 v[148:151], v196 offset:304
	ds_read_b128 v[176:179], v196 offset:320
	ds_read_b128 v[180:183], v196 offset:336
	ds_read_b128 v[184:187], v196 offset:352
	ds_read_b128 v[188:191], v196 offset:368
	s_waitcnt lgkmcnt(7)
	v_pk_fma_f32 v[158:159], v[0:1], v[136:137], 0 op_sel_hi:[1,1,0]
	v_pk_fma_f32 v[160:161], v[2:3], v[138:139], 0 op_sel_hi:[1,1,0]
	ds_read_b128 v[136:139], v196 offset:384
	s_waitcnt lgkmcnt(7)
	v_pk_fma_f32 v[158:159], v[4:5], v[140:141], v[158:159]
	v_pk_fma_f32 v[160:161], v[6:7], v[142:143], v[160:161]
	ds_read_b128 v[140:143], v196 offset:400
	s_waitcnt lgkmcnt(7)
	v_pk_fma_f32 v[158:159], v[8:9], v[144:145], v[158:159]
	v_pk_fma_f32 v[160:161], v[10:11], v[146:147], v[160:161]
	ds_read_b128 v[144:147], v196 offset:416
	s_waitcnt lgkmcnt(7)
	v_pk_fma_f32 v[158:159], v[12:13], v[148:149], v[158:159]
	v_pk_fma_f32 v[160:161], v[14:15], v[150:151], v[160:161]
	ds_read_b128 v[148:151], v196 offset:432
	s_waitcnt lgkmcnt(7)
	v_pk_fma_f32 v[158:159], v[16:17], v[176:177], v[158:159]
	v_pk_fma_f32 v[160:161], v[18:19], v[178:179], v[160:161]
	ds_read_b128 v[176:179], v196 offset:448
	s_waitcnt lgkmcnt(7)
	v_pk_fma_f32 v[158:159], v[20:21], v[180:181], v[158:159]
	v_pk_fma_f32 v[160:161], v[22:23], v[182:183], v[160:161]
	ds_read_b128 v[180:183], v196 offset:464
	s_waitcnt lgkmcnt(7)
	v_pk_fma_f32 v[158:159], v[24:25], v[184:185], v[158:159]
	v_pk_fma_f32 v[160:161], v[26:27], v[186:187], v[160:161]
	ds_read_b128 v[184:187], v196 offset:480
	s_waitcnt lgkmcnt(7)
	v_pk_fma_f32 v[158:159], v[28:29], v[188:189], v[158:159]
	v_pk_fma_f32 v[160:161], v[30:31], v[190:191], v[160:161]
	ds_read_b128 v[188:191], v196 offset:496
	s_waitcnt lgkmcnt(7)
	v_pk_fma_f32 v[158:159], v[32:33], v[136:137], v[158:159]
	v_pk_fma_f32 v[160:161], v[34:35], v[138:139], v[160:161]
	ds_read_b128 v[136:139], v196 offset:512
	s_waitcnt lgkmcnt(7)
	v_pk_fma_f32 v[158:159], v[36:37], v[140:141], v[158:159]
	v_pk_fma_f32 v[160:161], v[38:39], v[142:143], v[160:161]
	ds_read_b128 v[140:143], v196 offset:768
	s_waitcnt lgkmcnt(7)
	v_pk_fma_f32 v[158:159], v[40:41], v[144:145], v[158:159]
	v_pk_fma_f32 v[160:161], v[42:43], v[146:147], v[160:161]
	ds_read_b128 v[144:147], v196 offset:1024
	s_waitcnt lgkmcnt(7)
	v_pk_fma_f32 v[158:159], v[44:45], v[148:149], v[158:159]
	v_pk_fma_f32 v[160:161], v[46:47], v[150:151], v[160:161]
	ds_read_b128 v[148:151], v196 offset:528
	s_waitcnt lgkmcnt(7)
	v_pk_fma_f32 v[158:159], v[48:49], v[176:177], v[158:159]
	v_pk_fma_f32 v[160:161], v[50:51], v[178:179], v[160:161]
	ds_read_b128 v[176:179], v196 offset:784
	s_waitcnt lgkmcnt(7)
	v_pk_fma_f32 v[158:159], v[52:53], v[180:181], v[158:159]
	v_pk_fma_f32 v[160:161], v[54:55], v[182:183], v[160:161]
	ds_read_b128 v[180:183], v196 offset:1040
	s_waitcnt lgkmcnt(7)
	v_pk_fma_f32 v[158:159], v[56:57], v[184:185], v[158:159]
	v_pk_fma_f32 v[160:161], v[58:59], v[186:187], v[160:161]
	ds_read_b128 v[184:187], v196 offset:544
	s_waitcnt lgkmcnt(7)
	v_pk_fma_f32 v[158:159], v[60:61], v[188:189], v[158:159]
	v_pk_fma_f32 v[160:161], v[62:63], v[190:191], v[160:161]
	ds_read_b128 v[188:191], v196 offset:800
	v_add_f32_e32 v192, v158, v159
	v_add_f32_e32 v198, v160, v161
	v_add_f32_e32 v192, v198, v192
	s_waitcnt lgkmcnt(7)
	v_pk_fma_f32 v[0:1], v[136:137], v[192:193], v[0:1] op_sel_hi:[1,0,1] neg_lo:[0,1,0] neg_hi:[0,1,0]
	v_pk_fma_f32 v[2:3], v[138:139], v[192:193], v[2:3] op_sel_hi:[1,0,1] neg_lo:[0,1,0] neg_hi:[0,1,0]
	ds_read_b128 v[136:139], v196 offset:1056
	s_waitcnt lgkmcnt(7)
	v_pk_fma_f32 v[0:1], v[194:195], v[140:141], v[0:1] op_sel_hi:[0,1,1]
	v_pk_fma_f32 v[2:3], v[194:195], v[142:143], v[2:3] op_sel_hi:[0,1,1]
	ds_read_b128 v[140:143], v196 offset:560
	s_waitcnt lgkmcnt(7)
	v_pk_fma_f32 v[162:163], v[144:145], v[0:1], 0 op_sel_hi:[1,1,0]
	v_pk_fma_f32 v[164:165], v[146:147], v[2:3], 0 op_sel_hi:[1,1,0]
	ds_read_b128 v[144:147], v196 offset:816
	s_waitcnt lgkmcnt(7)
	v_pk_fma_f32 v[4:5], v[148:149], v[192:193], v[4:5] op_sel_hi:[1,0,1] neg_lo:[0,1,0] neg_hi:[0,1,0]
	v_pk_fma_f32 v[6:7], v[150:151], v[192:193], v[6:7] op_sel_hi:[1,0,1] neg_lo:[0,1,0] neg_hi:[0,1,0]
	ds_read_b128 v[148:151], v196 offset:1072
	s_waitcnt lgkmcnt(7)
	v_pk_fma_f32 v[4:5], v[194:195], v[176:177], v[4:5] op_sel_hi:[0,1,1]
	v_pk_fma_f32 v[6:7], v[194:195], v[178:179], v[6:7] op_sel_hi:[0,1,1]
	ds_read_b128 v[176:179], v196 offset:576
	s_waitcnt lgkmcnt(7)
	v_pk_fma_f32 v[162:163], v[180:181], v[4:5], v[162:163]
	v_pk_fma_f32 v[164:165], v[182:183], v[6:7], v[164:165]
	ds_read_b128 v[180:183], v196 offset:832
	s_waitcnt lgkmcnt(7)
	v_pk_fma_f32 v[8:9], v[184:185], v[192:193], v[8:9] op_sel_hi:[1,0,1] neg_lo:[0,1,0] neg_hi:[0,1,0]
	v_pk_fma_f32 v[10:11], v[186:187], v[192:193], v[10:11] op_sel_hi:[1,0,1] neg_lo:[0,1,0] neg_hi:[0,1,0]
	ds_read_b128 v[184:187], v196 offset:1088
	s_waitcnt lgkmcnt(7)
	v_pk_fma_f32 v[8:9], v[194:195], v[188:189], v[8:9] op_sel_hi:[0,1,1]
	v_pk_fma_f32 v[10:11], v[194:195], v[190:191], v[10:11] op_sel_hi:[0,1,1]
	ds_read_b128 v[188:191], v196 offset:592
	s_waitcnt lgkmcnt(7)
	v_pk_fma_f32 v[162:163], v[136:137], v[8:9], v[162:163]
	v_pk_fma_f32 v[164:165], v[138:139], v[10:11], v[164:165]
	ds_read_b128 v[136:139], v196 offset:848
	s_waitcnt lgkmcnt(7)
	v_pk_fma_f32 v[12:13], v[140:141], v[192:193], v[12:13] op_sel_hi:[1,0,1] neg_lo:[0,1,0] neg_hi:[0,1,0]
	v_pk_fma_f32 v[14:15], v[142:143], v[192:193], v[14:15] op_sel_hi:[1,0,1] neg_lo:[0,1,0] neg_hi:[0,1,0]
	ds_read_b128 v[140:143], v196 offset:1104
	s_waitcnt lgkmcnt(7)
; #define RW_LD_UPD(buf, qb) do { _Pragma("unroll") for (int q_ = 0; q_ < UB; ++q_) { const int qq_ = UB * (qb) + q_; \
;                 wq[buf][q_] = *(const LAS f32x4*)(st + 4 * qq_); bq[buf][q_] = *(const LAS f32x4*)(st + 128 + 4 * qq_); kq[buf][q_] = *(const LAS f32x4*)(st + 192 + 4 * qq_); \
;                 if (MODE == 1) rq[buf][q_] = *(const LAS f32x4*)(st + 256 + 4 * qq_); } } while (0)
; template <int MODE> __device__ __forceinline__ void rwkv_item(const Params& P, int e, int c, int h, LAS float* slab, int lane) {
;     ...
;             for (int qb = 0; qb < NUB; ++qb) {
;                 if (NB == 2) { if (qb + 1 < NUB) RW_LD_UPD((qb + 1) & 1, qb + 1); } else RW_LD_UPD(0, qb);
;                 __builtin_amdgcn_sched_barrier(0);
; #pragma unroll
;                 for (int q = 0; q < UB; ++q) {
;                     const int qq = UB * qb + q;
;                     const f32x4 w4 = wq[qb & (NB - 1)][q], b4 = bq[qb & (NB - 1)][q], k4 = kq[qb & (NB - 1)][q];
;                     if (MODE == 0) {
;                         S2[2 * qq] = S2[2 * qq] * (f32x2){w4.x, w4.y} + (f32x2){b4.x, b4.y} * nsk;
;                         S2[2 * qq + 1] = S2[2 * qq + 1] * (f32x2){w4.z, w4.w} + (f32x2){b4.z, b4.w} * nsk;
;                         C2[2 * qq] = C2[2 * qq] * (f32x2){w4.x, w4.y} + (f32x2){b4.x, b4.y} * nskC + (f32x2){k4.x, k4.y} * v;
;                         C2[2 * qq + 1] = C2[2 * qq + 1] * (f32x2){w4.z, w4.w} + (f32x2){b4.z, b4.w} * nskC + (f32x2){k4.z, k4.w} * v;
;                     } else {
;                         S2[2 * qq] = S2[2 * qq] * (f32x2){w4.x, w4.y} + (f32x2){b4.x, b4.y} * nsk + (f32x2){k4.x, k4.y} * v;
;                         S2[2 * qq + 1] = S2[2 * qq + 1] * (f32x2){w4.z, w4.w} + (f32x2){b4.z, b4.w} * nsk + (f32x2){k4.z, k4.w} * v;
;                         const f32x4 r4 = rq[qb & (NB - 1)][q]; y0 += S2[2 * qq] * (f32x2){r4.x, r4.y}; y1 += S2[2 * qq + 1] * (f32x2){r4.z, r4.w};
	v_pk_fma_f32 v[12:13], v[194:195], v[144:145], v[12:13] op_sel_hi:[0,1,1]
	v_pk_fma_f32 v[14:15], v[194:195], v[146:147], v[14:15] op_sel_hi:[0,1,1]
	ds_read_b128 v[144:147], v196 offset:608
	s_waitcnt lgkmcnt(7)
	v_pk_fma_f32 v[162:163], v[148:149], v[12:13], v[162:163]
	v_pk_fma_f32 v[164:165], v[150:151], v[14:15], v[164:165]
	ds_read_b128 v[148:151], v196 offset:864
	s_waitcnt lgkmcnt(7)
	v_pk_fma_f32 v[16:17], v[176:177], v[192:193], v[16:17] op_sel_hi:[1,0,1] neg_lo:[0,1,0] neg_hi:[0,1,0]
	v_pk_fma_f32 v[18:19], v[178:179], v[192:193], v[18:19] op_sel_hi:[1,0,1] neg_lo:[0,1,0] neg_hi:[0,1,0]
	ds_read_b128 v[176:179], v196 offset:1120
	s_waitcnt lgkmcnt(7)
	v_pk_fma_f32 v[16:17], v[194:195], v[180:181], v[16:17] op_sel_hi:[0,1,1]
	v_pk_fma_f32 v[18:19], v[194:195], v[182:183], v[18:19] op_sel_hi:[0,1,1]
	ds_read_b128 v[180:183], v196 offset:624
	s_waitcnt lgkmcnt(7)
	v_pk_fma_f32 v[162:163], v[184:185], v[16:17], v[162:163]
	v_pk_fma_f32 v[164:165], v[186:187], v[18:19], v[164:165]
	ds_read_b128 v[184:187], v196 offset:880
	s_waitcnt lgkmcnt(7)
	v_pk_fma_f32 v[20:21], v[188:189], v[192:193], v[20:21] op_sel_hi:[1,0,1] neg_lo:[0,1,0] neg_hi:[0,1,0]
	v_pk_fma_f32 v[22:23], v[190:191], v[192:193], v[22:23] op_sel_hi:[1,0,1] neg_lo:[0,1,0] neg_hi:[0,1,0]
	ds_read_b128 v[188:191], v196 offset:1136
	s_waitcnt lgkmcnt(7)
	v_pk_fma_f32 v[20:21], v[194:195], v[136:137], v[20:21] op_sel_hi:[0,1,1]
	v_pk_fma_f32 v[22:23], v[194:195], v[138:139], v[22:23] op_sel_hi:[0,1,1]
	ds_read_b128 v[136:139], v196 offset:640
	s_waitcnt lgkmcnt(7)
	v_pk_fma_f32 v[162:163], v[140:141], v[20:21], v[162:163]
	v_pk_fma_f32 v[164:165], v[142:143], v[22:23], v[164:165]
	ds_read_b128 v[140:143], v196 offset:896
	s_waitcnt lgkmcnt(7)
	v_pk_fma_f32 v[24:25], v[144:145], v[192:193], v[24:25] op_sel_hi:[1,0,1] neg_lo:[0,1,0] neg_hi:[0,1,0]
	v_pk_fma_f32 v[26:27], v[146:147], v[192:193], v[26:27] op_sel_hi:[1,0,1] neg_lo:[0,1,0] neg_hi:[0,1,0]
	ds_read_b128 v[144:147], v196 offset:1152
	s_waitcnt lgkmcnt(7)
	v_pk_fma_f32 v[24:25], v[194:195], v[148:149], v[24:25] op_sel_hi:[0,1,1]
	v_pk_fma_f32 v[26:27], v[194:195], v[150:151], v[26:27] op_sel_hi:[0,1,1]
	ds_read_b128 v[148:151], v196 offset:656
	s_waitcnt lgkmcnt(7)
	v_pk_fma_f32 v[162:163], v[176:177], v[24:25], v[162:163]
	v_pk_fma_f32 v[164:165], v[178:179], v[26:27], v[164:165]
	ds_read_b128 v[176:179], v196 offset:912
	s_waitcnt lgkmcnt(7)
	v_pk_fma_f32 v[28:29], v[180:181], v[192:193], v[28:29] op_sel_hi:[1,0,1] neg_lo:[0,1,0] neg_hi:[0,1,0]
	v_pk_fma_f32 v[30:31], v[182:183], v[192:193], v[30:31] op_sel_hi:[1,0,1] neg_lo:[0,1,0] neg_hi:[0,1,0]
	ds_read_b128 v[180:183], v196 offset:1168
	s_waitcnt lgkmcnt(7)
	v_pk_fma_f32 v[28:29], v[194:195], v[184:185], v[28:29] op_sel_hi:[0,1,1]
	v_pk_fma_f32 v[30:31], v[194:195], v[186:187], v[30:31] op_sel_hi:[0,1,1]
	ds_read_b128 v[184:187], v196 offset:672
	s_waitcnt lgkmcnt(7)
	v_pk_fma_f32 v[162:163], v[188:189], v[28:29], v[162:163]
	v_pk_fma_f32 v[164:165], v[190:191], v[30:31], v[164:165]
	ds_read_b128 v[188:191], v196 offset:928
	s_waitcnt lgkmcnt(7)
	v_pk_fma_f32 v[32:33], v[136:137], v[192:193], v[32:33] op_sel_hi:[1,0,1] neg_lo:[0,1,0] neg_hi:[0,1,0]
	v_pk_fma_f32 v[34:35], v[138:139], v[192:193], v[34:35] op_sel_hi:[1,0,1] neg_lo:[0,1,0] neg_hi:[0,1,0]
	ds_read_b128 v[136:139], v196 offset:1184
	s_waitcnt lgkmcnt(7)
	v_pk_fma_f32 v[32:33], v[194:195], v[140:141], v[32:33] op_sel_hi:[0,1,1]
	v_pk_fma_f32 v[34:35], v[194:195], v[142:143], v[34:35] op_sel_hi:[0,1,1]
	ds_read_b128 v[140:143], v196 offset:688
	s_waitcnt lgkmcnt(7)
	v_pk_fma_f32 v[162:163], v[144:145], v[32:33], v[162:163]
	v_pk_fma_f32 v[164:165], v[146:147], v[34:35], v[164:165]
	ds_read_b128 v[144:147], v196 offset:944
	s_waitcnt lgkmcnt(7)
	v_pk_fma_f32 v[36:37], v[148:149], v[192:193], v[36:37] op_sel_hi:[1,0,1] neg_lo:[0,1,0] neg_hi:[0,1,0]
	v_pk_fma_f32 v[38:39], v[150:151], v[192:193], v[38:39] op_sel_hi:[1,0,1] neg_lo:[0,1,0] neg_hi:[0,1,0]
	ds_read_b128 v[148:151], v196 offset:1200
	s_waitcnt lgkmcnt(7)
	v_pk_fma_f32 v[36:37], v[194:195], v[176:177], v[36:37] op_sel_hi:[0,1,1]
	v_pk_fma_f32 v[38:39], v[194:195], v[178:179], v[38:39] op_sel_hi:[0,1,1]
	ds_read_b128 v[176:179], v196 offset:704
	s_waitcnt lgkmcnt(7)
	v_pk_fma_f32 v[162:163], v[180:181], v[36:37], v[162:163]
	v_pk_fma_f32 v[164:165], v[182:183], v[38:39], v[164:165]
	ds_read_b128 v[180:183], v196 offset:960
	s_waitcnt lgkmcnt(7)
	v_pk_fma_f32 v[40:41], v[184:185], v[192:193], v[40:41] op_sel_hi:[1,0,1] neg_lo:[0,1,0] neg_hi:[0,1,0]
	v_pk_fma_f32 v[42:43], v[186:187], v[192:193], v[42:43] op_sel_hi:[1,0,1] neg_lo:[0,1,0] neg_hi:[0,1,0]
	ds_read_b128 v[184:187], v196 offset:1216
	s_waitcnt lgkmcnt(7)
	v_pk_fma_f32 v[40:41], v[194:195], v[188:189], v[40:41] op_sel_hi:[0,1,1]
	v_pk_fma_f32 v[42:43], v[194:195], v[190:191], v[42:43] op_sel_hi:[0,1,1]
	ds_read_b128 v[188:191], v196 offset:720
	s_waitcnt lgkmcnt(7)
	v_pk_fma_f32 v[162:163], v[136:137], v[40:41], v[162:163]
	v_pk_fma_f32 v[164:165], v[138:139], v[42:43], v[164:165]
	ds_read_b128 v[136:139], v196 offset:976
	s_waitcnt lgkmcnt(7)
	v_pk_fma_f32 v[44:45], v[140:141], v[192:193], v[44:45] op_sel_hi:[1,0,1] neg_lo:[0,1,0] neg_hi:[0,1,0]
	v_pk_fma_f32 v[46:47], v[142:143], v[192:193], v[46:47] op_sel_hi:[1,0,1] neg_lo:[0,1,0] neg_hi:[0,1,0]
	ds_read_b128 v[140:143], v196 offset:1232
	s_waitcnt lgkmcnt(7)
	v_pk_fma_f32 v[44:45], v[194:195], v[144:145], v[44:45] op_sel_hi:[0,1,1]
	v_pk_fma_f32 v[46:47], v[194:195], v[146:147], v[46:47] op_sel_hi:[0,1,1]
	ds_read_b128 v[144:147], v196 offset:736
	s_waitcnt lgkmcnt(7)
; #define LAS __attribute__((address_space(3)))
; template <int MODE> __device__ __forceinline__ void rwkv_item(const Params& P, int e, int c, int h, LAS float* slab, int lane) {
;     ...
;             for (int qb = 0; qb < NUB; ++qb) {
;                 if (NB == 2) { if (qb + 1 < NUB) RW_LD_UPD((qb + 1) & 1, qb + 1); } else RW_LD_UPD(0, qb);
;                 __builtin_amdgcn_sched_barrier(0);
; #pragma unroll
;                 for (int q = 0; q < UB; ++q) {
;                     const int qq = UB * qb + q;
;                     const f32x4 w4 = wq[qb & (NB - 1)][q], b4 = bq[qb & (NB - 1)][q], k4 = kq[qb & (NB - 1)][q];
;                     if (MODE == 0) {
;                         S2[2 * qq] = S2[2 * qq] * (f32x2){w4.x, w4.y} + (f32x2){b4.x, b4.y} * nsk;
;                         S2[2 * qq + 1] = S2[2 * qq + 1] * (f32x2){w4.z, w4.w} + (f32x2){b4.z, b4.w} * nsk;
;                         C2[2 * qq] = C2[2 * qq] * (f32x2){w4.x, w4.y} + (f32x2){b4.x, b4.y} * nskC + (f32x2){k4.x, k4.y} * v;
;                         C2[2 * qq + 1] = C2[2 * qq + 1] * (f32x2){w4.z, w4.w} + (f32x2){b4.z, b4.w} * nskC + (f32x2){k4.z, k4.w} * v;
;                     } else {
;                         S2[2 * qq] = S2[2 * qq] * (f32x2){w4.x, w4.y} + (f32x2){b4.x, b4.y} * nsk + (f32x2){k4.x, k4.y} * v;
;                         S2[2 * qq + 1] = S2[2 * qq + 1] * (f32x2){w4.z, w4.w} + (f32x2){b4.z, b4.w} * nsk + (f32x2){k4.z, k4.w} * v;
;                         const f32x4 r4 = rq[qb & (NB - 1)][q]; y0 += S2[2 * qq] * (f32x2){r4.x, r4.y}; y1 += S2[2 * qq + 1] * (f32x2){r4.z, r4.w};
;                     }
;                 }
;                 __builtin_amdgcn_sched_barrier(0);
;             }
;     ...
;             if (MODE == 1) ((LAS float*)st)[lane] = (y0.x + y0.y) + (y1.x + y1.y);
;         }
;         if (MODE == 1) {
;             LDS_WAIT();
; #pragma unroll
;             for (int s = 0; s < SB; ++s) {
;                 const LAS float* st = slab + s * 512;
;                 const float y = st[lane], v = st[320 + lane];
;                 const float mean = wave_sum(y) * (1.f / 64.f), d = y - mean;
;                 const float var = wave_sum(d * d) * (1.f / 64.f);
;                 const float yn = d * frsq(var + 64e-5f) * lnw + lnb;
;                 MIX[(size_t)(tb + s) * D + ch] = (bf16)f2bf((yn + st[384 + lane] * v) * st[448 + lane]);
	v_pk_fma_f32 v[162:163], v[148:149], v[44:45], v[162:163]
	v_pk_fma_f32 v[164:165], v[150:151], v[46:47], v[164:165]
	ds_read_b128 v[148:151], v196 offset:992
	s_waitcnt lgkmcnt(7)
	v_pk_fma_f32 v[48:49], v[176:177], v[192:193], v[48:49] op_sel_hi:[1,0,1] neg_lo:[0,1,0] neg_hi:[0,1,0]
	v_pk_fma_f32 v[50:51], v[178:179], v[192:193], v[50:51] op_sel_hi:[1,0,1] neg_lo:[0,1,0] neg_hi:[0,1,0]
	ds_read_b128 v[176:179], v196 offset:1248
	s_waitcnt lgkmcnt(7)
	v_pk_fma_f32 v[48:49], v[194:195], v[180:181], v[48:49] op_sel_hi:[0,1,1]
	v_pk_fma_f32 v[50:51], v[194:195], v[182:183], v[50:51] op_sel_hi:[0,1,1]
	ds_read_b128 v[180:183], v196 offset:752
	s_waitcnt lgkmcnt(7)
	v_pk_fma_f32 v[162:163], v[184:185], v[48:49], v[162:163]
	v_pk_fma_f32 v[164:165], v[186:187], v[50:51], v[164:165]
	ds_read_b128 v[184:187], v196 offset:1008
	s_waitcnt lgkmcnt(7)
	v_pk_fma_f32 v[52:53], v[188:189], v[192:193], v[52:53] op_sel_hi:[1,0,1] neg_lo:[0,1,0] neg_hi:[0,1,0]
	v_pk_fma_f32 v[54:55], v[190:191], v[192:193], v[54:55] op_sel_hi:[1,0,1] neg_lo:[0,1,0] neg_hi:[0,1,0]
	ds_read_b128 v[188:191], v196 offset:1264
	s_waitcnt lgkmcnt(7)
	v_pk_fma_f32 v[52:53], v[194:195], v[136:137], v[52:53] op_sel_hi:[0,1,1]
	v_pk_fma_f32 v[54:55], v[194:195], v[138:139], v[54:55] op_sel_hi:[0,1,1]
	s_waitcnt lgkmcnt(6)
	v_pk_fma_f32 v[162:163], v[140:141], v[52:53], v[162:163]
	v_pk_fma_f32 v[164:165], v[142:143], v[54:55], v[164:165]
	s_waitcnt lgkmcnt(5)
	v_pk_fma_f32 v[56:57], v[144:145], v[192:193], v[56:57] op_sel_hi:[1,0,1] neg_lo:[0,1,0] neg_hi:[0,1,0]
	v_pk_fma_f32 v[58:59], v[146:147], v[192:193], v[58:59] op_sel_hi:[1,0,1] neg_lo:[0,1,0] neg_hi:[0,1,0]
	s_waitcnt lgkmcnt(4)
	v_pk_fma_f32 v[56:57], v[194:195], v[148:149], v[56:57] op_sel_hi:[0,1,1]
	v_pk_fma_f32 v[58:59], v[194:195], v[150:151], v[58:59] op_sel_hi:[0,1,1]
	s_waitcnt lgkmcnt(3)
	v_pk_fma_f32 v[162:163], v[176:177], v[56:57], v[162:163]
	v_pk_fma_f32 v[164:165], v[178:179], v[58:59], v[164:165]
	s_waitcnt lgkmcnt(2)
	v_pk_fma_f32 v[60:61], v[180:181], v[192:193], v[60:61] op_sel_hi:[1,0,1] neg_lo:[0,1,0] neg_hi:[0,1,0]
	v_pk_fma_f32 v[62:63], v[182:183], v[192:193], v[62:63] op_sel_hi:[1,0,1] neg_lo:[0,1,0] neg_hi:[0,1,0]
	s_waitcnt lgkmcnt(1)
	v_pk_fma_f32 v[60:61], v[194:195], v[184:185], v[60:61] op_sel_hi:[0,1,1]
	v_pk_fma_f32 v[62:63], v[194:195], v[186:187], v[62:63] op_sel_hi:[0,1,1]
	s_waitcnt lgkmcnt(0)
	v_pk_fma_f32 v[162:163], v[188:189], v[60:61], v[162:163]
	v_pk_fma_f32 v[164:165], v[190:191], v[62:63], v[164:165]
	v_add_f32_e32 v198, v162, v163
	v_add_f32_e32 v192, v164, v165
	v_add_f32_e32 v198, v192, v198
	s_addk_i32 s11, 0x800
	ds_write_b32 v197, v198
	s_cmpk_eq_i32 s11, 0x4000
	s_cbranch_scc0 .Lm1_step
	s_waitcnt lgkmcnt(0)
	s_waitcnt vmcnt(48)
	ds_read2st64_b32 v[200:201], v109 offset0:0 offset1:5
	ds_read2st64_b32 v[204:205], v109 offset0:6 offset1:7
	s_waitcnt lgkmcnt(1)
	v_add_f32_dpp v202, v200, v200 quad_perm:[1,0,3,2] row_mask:0xf bank_mask:0xf bound_ctrl:1
	s_nop 1
	v_add_f32_dpp v202, v202, v202 quad_perm:[2,3,0,1] row_mask:0xf bank_mask:0xf bound_ctrl:1
	s_nop 1
	v_add_f32_dpp v202, v202, v202 row_half_mirror row_mask:0xf bank_mask:0xf bound_ctrl:1
	s_nop 1
	v_add_f32_dpp v202, v202, v202 row_mirror row_mask:0xf bank_mask:0xf bound_ctrl:1
	s_nop 0
	v_readlane_b32 s8, v202, 16
	v_readlane_b32 s10, v202, 48
	v_readlane_b32 s0, v202, 0
	v_readlane_b32 s9, v202, 32
	v_mov_b32_e32 v202, s8
	v_mov_b32_e32 v203, s10
	v_add_f32_e32 v202, s0, v202
	v_add_f32_e32 v203, s9, v203
	v_add_f32_e32 v202, v202, v203
	v_fmamk_f32 v200, v202, 0xbc800000, v200
	v_mul_f32_e32 v202, v200, v200
	s_nop 1
	v_mov_b32_dpp v202, v202 quad_perm:[1,0,3,2] row_mask:0xf bank_mask:0xf bound_ctrl:1
	v_fmac_f32_e32 v202, v200, v200
	s_nop 1
	v_add_f32_dpp v202, v202, v202 quad_perm:[2,3,0,1] row_mask:0xf bank_mask:0xf bound_ctrl:1
	s_nop 1
	v_add_f32_dpp v202, v202, v202 row_half_mirror row_mask:0xf bank_mask:0xf bound_ctrl:1
	s_nop 1
	v_add_f32_dpp v202, v202, v202 row_mirror row_mask:0xf bank_mask:0xf bound_ctrl:1
	s_nop 0
	v_readlane_b32 s8, v202, 16
	v_readlane_b32 s10, v202, 48
	v_readlane_b32 s0, v202, 0
	v_readlane_b32 s9, v202, 32
	v_mov_b32_e32 v202, s8
	v_mov_b32_e32 v203, s10
	v_add_f32_e32 v202, s0, v202
	v_add_f32_e32 v203, s9, v203
	v_add_f32_e32 v202, v202, v203
	v_fmamk_f32 v202, v202, 0x3c800000, v221
	v_rsq_f32_e32 v202, v202
	v_add_u32_e32 v207, 0x0, v113
	v_mul_f32_e32 v200, v200, v202
	v_fma_f32 v200, v120, v200, v121
	s_waitcnt lgkmcnt(0)
	v_fmac_f32_e32 v200, v201, v204
	v_mul_f32_e32 v200, v205, v200
	v_bfe_u32 v203, v200, 16, 1
	v_add3_u32 v206, v200, v203, s33
	global_store_short_d16_hi v207, v206, s[70:71]
	ds_read2st64_b32 v[200:201], v109 offset0:8 offset1:13
	ds_read2st64_b32 v[204:205], v109 offset0:14 offset1:15
	s_waitcnt lgkmcnt(1)
	v_add_f32_dpp v202, v200, v200 quad_perm:[1,0,3,2] row_mask:0xf bank_mask:0xf bound_ctrl:1
	s_nop 1
	v_add_f32_dpp v202, v202, v202 quad_perm:[2,3,0,1] row_mask:0xf bank_mask:0xf bound_ctrl:1
	s_nop 1
	v_add_f32_dpp v202, v202, v202 row_half_mirror row_mask:0xf bank_mask:0xf bound_ctrl:1
	s_nop 1
	v_add_f32_dpp v202, v202, v202 row_mirror row_mask:0xf bank_mask:0xf bound_ctrl:1
	s_nop 0
	v_readlane_b32 s8, v202, 16
	v_readlane_b32 s10, v202, 48
	v_readlane_b32 s0, v202, 0
	v_readlane_b32 s9, v202, 32
	v_mov_b32_e32 v202, s8
	v_mov_b32_e32 v203, s10
	v_add_f32_e32 v202, s0, v202
	v_add_f32_e32 v203, s9, v203
	v_add_f32_e32 v202, v202, v203
	v_fmamk_f32 v200, v202, 0xbc800000, v200
	v_mul_f32_e32 v202, v200, v200
	s_nop 1
	v_mov_b32_dpp v202, v202 quad_perm:[1,0,3,2] row_mask:0xf bank_mask:0xf bound_ctrl:1
	v_fmac_f32_e32 v202, v200, v200
	s_nop 1
	v_add_f32_dpp v202, v202, v202 quad_perm:[2,3,0,1] row_mask:0xf bank_mask:0xf bound_ctrl:1
	s_nop 1
	v_add_f32_dpp v202, v202, v202 row_half_mirror row_mask:0xf bank_mask:0xf bound_ctrl:1
	s_nop 1
	v_add_f32_dpp v202, v202, v202 row_mirror row_mask:0xf bank_mask:0xf bound_ctrl:1
	s_nop 0
	v_readlane_b32 s8, v202, 16
	v_readlane_b32 s10, v202, 48
	v_readlane_b32 s0, v202, 0
	v_readlane_b32 s9, v202, 32
	v_mov_b32_e32 v202, s8
	v_mov_b32_e32 v203, s10
	v_add_f32_e32 v202, s0, v202
	v_add_f32_e32 v203, s9, v203
	v_add_f32_e32 v202, v202, v203
	v_fmamk_f32 v202, v202, 0x3c800000, v221
	v_rsq_f32_e32 v202, v202
	v_add_u32_e32 v207, 0x800, v113
	v_mul_f32_e32 v200, v200, v202
	v_fma_f32 v200, v120, v200, v121
	s_waitcnt lgkmcnt(0)
; #define LAS __attribute__((address_space(3)))
; __device__ __forceinline__ unsigned f2bf(float f) { unsigned u = __float_as_uint(f); return (u + 0x7fffu + ((u >> 16) & 1u)) >> 16; }
; __device__ __forceinline__ float frsq(float x) { return __builtin_amdgcn_rsqf(x); }
; template <int MODE> __device__ __forceinline__ void rwkv_item(const Params& P, int e, int c, int h, LAS float* slab, int lane) {
;     ...
;             for (int s = 0; s < SB; ++s) {
;                 const LAS float* st = slab + s * 512;
;                 const float y = st[lane], v = st[320 + lane];
;                 const float mean = wave_sum(y) * (1.f / 64.f), d = y - mean;
;                 const float var = wave_sum(d * d) * (1.f / 64.f);
;                 const float yn = d * frsq(var + 64e-5f) * lnw + lnb;
;                 MIX[(size_t)(tb + s) * D + ch] = (bf16)f2bf((yn + st[384 + lane] * v) * st[448 + lane]);
;             }
	v_fmac_f32_e32 v200, v201, v204
	v_mul_f32_e32 v200, v205, v200
	v_bfe_u32 v203, v200, 16, 1
	v_add3_u32 v206, v200, v203, s33
	global_store_short_d16_hi v207, v206, s[70:71]
	ds_read2st64_b32 v[200:201], v109 offset0:16 offset1:21
	ds_read2st64_b32 v[204:205], v109 offset0:22 offset1:23
	s_waitcnt lgkmcnt(1)
	v_add_f32_dpp v202, v200, v200 quad_perm:[1,0,3,2] row_mask:0xf bank_mask:0xf bound_ctrl:1
	s_nop 1
	v_add_f32_dpp v202, v202, v202 quad_perm:[2,3,0,1] row_mask:0xf bank_mask:0xf bound_ctrl:1
	s_nop 1
	v_add_f32_dpp v202, v202, v202 row_half_mirror row_mask:0xf bank_mask:0xf bound_ctrl:1
	s_nop 1
	v_add_f32_dpp v202, v202, v202 row_mirror row_mask:0xf bank_mask:0xf bound_ctrl:1
	s_nop 0
	v_readlane_b32 s8, v202, 16
	v_readlane_b32 s10, v202, 48
	v_readlane_b32 s0, v202, 0
	v_readlane_b32 s9, v202, 32
	v_mov_b32_e32 v202, s8
	v_mov_b32_e32 v203, s10
	v_add_f32_e32 v202, s0, v202
	v_add_f32_e32 v203, s9, v203
	v_add_f32_e32 v202, v202, v203
	v_fmamk_f32 v200, v202, 0xbc800000, v200
	v_mul_f32_e32 v202, v200, v200
	s_nop 1
	v_mov_b32_dpp v202, v202 quad_perm:[1,0,3,2] row_mask:0xf bank_mask:0xf bound_ctrl:1
	v_fmac_f32_e32 v202, v200, v200
	s_nop 1
	v_add_f32_dpp v202, v202, v202 quad_perm:[2,3,0,1] row_mask:0xf bank_mask:0xf bound_ctrl:1
	s_nop 1
	v_add_f32_dpp v202, v202, v202 row_half_mirror row_mask:0xf bank_mask:0xf bound_ctrl:1
	s_nop 1
	v_add_f32_dpp v202, v202, v202 row_mirror row_mask:0xf bank_mask:0xf bound_ctrl:1
	s_nop 0
	v_readlane_b32 s8, v202, 16
	v_readlane_b32 s10, v202, 48
	v_readlane_b32 s0, v202, 0
	v_readlane_b32 s9, v202, 32
	v_mov_b32_e32 v202, s8
	v_mov_b32_e32 v203, s10
	v_add_f32_e32 v202, s0, v202
	v_add_f32_e32 v203, s9, v203
	v_add_f32_e32 v202, v202, v203
	v_fmamk_f32 v202, v202, 0x3c800000, v221
	v_rsq_f32_e32 v202, v202
	v_add_u32_e32 v207, 0x1000, v113
	v_mul_f32_e32 v200, v200, v202
	v_fma_f32 v200, v120, v200, v121
	s_waitcnt lgkmcnt(0)
	v_fmac_f32_e32 v200, v201, v204
	v_mul_f32_e32 v200, v205, v200
	v_bfe_u32 v203, v200, 16, 1
	v_add3_u32 v206, v200, v203, s33
	global_store_short_d16_hi v207, v206, s[70:71]
	ds_read2st64_b32 v[200:201], v109 offset0:24 offset1:29
	ds_read2st64_b32 v[204:205], v109 offset0:30 offset1:31
	s_waitcnt lgkmcnt(1)
	v_add_f32_dpp v202, v200, v200 quad_perm:[1,0,3,2] row_mask:0xf bank_mask:0xf bound_ctrl:1
	s_nop 1
	v_add_f32_dpp v202, v202, v202 quad_perm:[2,3,0,1] row_mask:0xf bank_mask:0xf bound_ctrl:1
	s_nop 1
	v_add_f32_dpp v202, v202, v202 row_half_mirror row_mask:0xf bank_mask:0xf bound_ctrl:1
	s_nop 1
	v_add_f32_dpp v202, v202, v202 row_mirror row_mask:0xf bank_mask:0xf bound_ctrl:1
	s_nop 0
	v_readlane_b32 s8, v202, 16
	v_readlane_b32 s10, v202, 48
	v_readlane_b32 s0, v202, 0
	v_readlane_b32 s9, v202, 32
	v_mov_b32_e32 v202, s8
	v_mov_b32_e32 v203, s10
	v_add_f32_e32 v202, s0, v202
	v_add_f32_e32 v203, s9, v203
	v_add_f32_e32 v202, v202, v203
	v_fmamk_f32 v200, v202, 0xbc800000, v200
	v_mul_f32_e32 v202, v200, v200
	s_nop 1
	v_mov_b32_dpp v202, v202 quad_perm:[1,0,3,2] row_mask:0xf bank_mask:0xf bound_ctrl:1
	v_fmac_f32_e32 v202, v200, v200
	s_nop 1
	v_add_f32_dpp v202, v202, v202 quad_perm:[2,3,0,1] row_mask:0xf bank_mask:0xf bound_ctrl:1
	s_nop 1
	v_add_f32_dpp v202, v202, v202 row_half_mirror row_mask:0xf bank_mask:0xf bound_ctrl:1
	s_nop 1
	v_add_f32_dpp v202, v202, v202 row_mirror row_mask:0xf bank_mask:0xf bound_ctrl:1
	s_nop 0
	v_readlane_b32 s8, v202, 16
	v_readlane_b32 s10, v202, 48
	v_readlane_b32 s0, v202, 0
	v_readlane_b32 s9, v202, 32
	v_mov_b32_e32 v202, s8
	v_mov_b32_e32 v203, s10
	v_add_f32_e32 v202, s0, v202
	v_add_f32_e32 v203, s9, v203
	v_add_f32_e32 v202, v202, v203
	v_fmamk_f32 v202, v202, 0x3c800000, v221
	v_rsq_f32_e32 v202, v202
	v_add_u32_e32 v207, 0x1800, v113
	v_mul_f32_e32 v200, v200, v202
	v_fma_f32 v200, v120, v200, v121
	s_waitcnt lgkmcnt(0)
	v_fmac_f32_e32 v200, v201, v204
	v_mul_f32_e32 v200, v205, v200
	v_bfe_u32 v203, v200, 16, 1
	v_add3_u32 v206, v200, v203, s33
	global_store_short_d16_hi v207, v206, s[70:71]
	ds_read2st64_b32 v[200:201], v109 offset0:32 offset1:37
	ds_read2st64_b32 v[204:205], v109 offset0:38 offset1:39
	s_waitcnt lgkmcnt(1)
	v_add_f32_dpp v202, v200, v200 quad_perm:[1,0,3,2] row_mask:0xf bank_mask:0xf bound_ctrl:1
	s_nop 1
	v_add_f32_dpp v202, v202, v202 quad_perm:[2,3,0,1] row_mask:0xf bank_mask:0xf bound_ctrl:1
	s_nop 1
	v_add_f32_dpp v202, v202, v202 row_half_mirror row_mask:0xf bank_mask:0xf bound_ctrl:1
	s_nop 1
	v_add_f32_dpp v202, v202, v202 row_mirror row_mask:0xf bank_mask:0xf bound_ctrl:1
	s_nop 0
	v_readlane_b32 s8, v202, 16
	v_readlane_b32 s10, v202, 48
	v_readlane_b32 s0, v202, 0
	v_readlane_b32 s9, v202, 32
	v_mov_b32_e32 v202, s8
	v_mov_b32_e32 v203, s10
	v_add_f32_e32 v202, s0, v202
	v_add_f32_e32 v203, s9, v203
	v_add_f32_e32 v202, v202, v203
	v_fmamk_f32 v200, v202, 0xbc800000, v200
	v_mul_f32_e32 v202, v200, v200
	s_nop 1
	v_mov_b32_dpp v202, v202 quad_perm:[1,0,3,2] row_mask:0xf bank_mask:0xf bound_ctrl:1
	v_fmac_f32_e32 v202, v200, v200
	s_nop 1
	v_add_f32_dpp v202, v202, v202 quad_perm:[2,3,0,1] row_mask:0xf bank_mask:0xf bound_ctrl:1
	s_nop 1
	v_add_f32_dpp v202, v202, v202 row_half_mirror row_mask:0xf bank_mask:0xf bound_ctrl:1
	s_nop 1
	v_add_f32_dpp v202, v202, v202 row_mirror row_mask:0xf bank_mask:0xf bound_ctrl:1
	s_nop 0
	v_readlane_b32 s8, v202, 16
	v_readlane_b32 s10, v202, 48
	v_readlane_b32 s0, v202, 0
	v_readlane_b32 s9, v202, 32
	v_mov_b32_e32 v202, s8
	v_mov_b32_e32 v203, s10
	v_add_f32_e32 v202, s0, v202
	v_add_f32_e32 v203, s9, v203
	v_add_f32_e32 v202, v202, v203
	v_fmamk_f32 v202, v202, 0x3c800000, v221
	v_rsq_f32_e32 v202, v202
	v_add_u32_e32 v207, 0x2000, v113
	v_mul_f32_e32 v200, v200, v202
	v_fma_f32 v200, v120, v200, v121
	s_waitcnt lgkmcnt(0)
; #define LAS __attribute__((address_space(3)))
; __device__ __forceinline__ unsigned f2bf(float f) { unsigned u = __float_as_uint(f); return (u + 0x7fffu + ((u >> 16) & 1u)) >> 16; }
; __device__ __forceinline__ float frsq(float x) { return __builtin_amdgcn_rsqf(x); }
; #define LDS_WAIT() asm volatile("s_waitcnt lgkmcnt(0)" ::: "memory")
; template <int MODE> __device__ __forceinline__ void rwkv_item(const Params& P, int e, int c, int h, LAS float* slab, int lane) {
;     ...
;         if (MODE == 1) {
;             LDS_WAIT();
; #pragma unroll
;             for (int s = 0; s < SB; ++s) {
;                 const LAS float* st = slab + s * 512;
;                 const float y = st[lane], v = st[320 + lane];
;                 const float mean = wave_sum(y) * (1.f / 64.f), d = y - mean;
;                 const float var = wave_sum(d * d) * (1.f / 64.f);
;                 const float yn = d * frsq(var + 64e-5f) * lnw + lnb;
;                 MIX[(size_t)(tb + s) * D + ch] = (bf16)f2bf((yn + st[384 + lane] * v) * st[448 + lane]);
;             }
;         }
;         LDS_WAIT();
;     }
	v_fmac_f32_e32 v200, v201, v204
	v_mul_f32_e32 v200, v205, v200
	v_bfe_u32 v203, v200, 16, 1
	v_add3_u32 v206, v200, v203, s33
	global_store_short_d16_hi v207, v206, s[70:71]
	ds_read2st64_b32 v[200:201], v109 offset0:40 offset1:45
	ds_read2st64_b32 v[204:205], v109 offset0:46 offset1:47
	s_waitcnt lgkmcnt(1)
	v_add_f32_dpp v202, v200, v200 quad_perm:[1,0,3,2] row_mask:0xf bank_mask:0xf bound_ctrl:1
	s_nop 1
	v_add_f32_dpp v202, v202, v202 quad_perm:[2,3,0,1] row_mask:0xf bank_mask:0xf bound_ctrl:1
	s_nop 1
	v_add_f32_dpp v202, v202, v202 row_half_mirror row_mask:0xf bank_mask:0xf bound_ctrl:1
	s_nop 1
	v_add_f32_dpp v202, v202, v202 row_mirror row_mask:0xf bank_mask:0xf bound_ctrl:1
	s_nop 0
	v_readlane_b32 s8, v202, 16
	v_readlane_b32 s10, v202, 48
	v_readlane_b32 s0, v202, 0
	v_readlane_b32 s9, v202, 32
	v_mov_b32_e32 v202, s8
	v_mov_b32_e32 v203, s10
	v_add_f32_e32 v202, s0, v202
	v_add_f32_e32 v203, s9, v203
	v_add_f32_e32 v202, v202, v203
	v_fmamk_f32 v200, v202, 0xbc800000, v200
	v_mul_f32_e32 v202, v200, v200
	s_nop 1
	v_mov_b32_dpp v202, v202 quad_perm:[1,0,3,2] row_mask:0xf bank_mask:0xf bound_ctrl:1
	v_fmac_f32_e32 v202, v200, v200
	s_nop 1
	v_add_f32_dpp v202, v202, v202 quad_perm:[2,3,0,1] row_mask:0xf bank_mask:0xf bound_ctrl:1
	s_nop 1
	v_add_f32_dpp v202, v202, v202 row_half_mirror row_mask:0xf bank_mask:0xf bound_ctrl:1
	s_nop 1
	v_add_f32_dpp v202, v202, v202 row_mirror row_mask:0xf bank_mask:0xf bound_ctrl:1
	s_nop 0
	v_readlane_b32 s8, v202, 16
	v_readlane_b32 s10, v202, 48
	v_readlane_b32 s0, v202, 0
	v_readlane_b32 s9, v202, 32
	v_mov_b32_e32 v202, s8
	v_mov_b32_e32 v203, s10
	v_add_f32_e32 v202, s0, v202
	v_add_f32_e32 v203, s9, v203
	v_add_f32_e32 v202, v202, v203
	v_fmamk_f32 v202, v202, 0x3c800000, v221
	v_rsq_f32_e32 v202, v202
	v_add_u32_e32 v207, 0x2800, v113
	v_mul_f32_e32 v200, v200, v202
	v_fma_f32 v200, v120, v200, v121
	s_waitcnt lgkmcnt(0)
	v_fmac_f32_e32 v200, v201, v204
	v_mul_f32_e32 v200, v205, v200
	v_bfe_u32 v203, v200, 16, 1
	v_add3_u32 v206, v200, v203, s33
	global_store_short_d16_hi v207, v206, s[70:71]
	ds_read2st64_b32 v[200:201], v109 offset0:48 offset1:53
	ds_read2st64_b32 v[204:205], v109 offset0:54 offset1:55
	s_waitcnt lgkmcnt(1)
	v_add_f32_dpp v202, v200, v200 quad_perm:[1,0,3,2] row_mask:0xf bank_mask:0xf bound_ctrl:1
	s_nop 1
	v_add_f32_dpp v202, v202, v202 quad_perm:[2,3,0,1] row_mask:0xf bank_mask:0xf bound_ctrl:1
	s_nop 1
	v_add_f32_dpp v202, v202, v202 row_half_mirror row_mask:0xf bank_mask:0xf bound_ctrl:1
	s_nop 1
	v_add_f32_dpp v202, v202, v202 row_mirror row_mask:0xf bank_mask:0xf bound_ctrl:1
	s_nop 0
	v_readlane_b32 s8, v202, 16
	v_readlane_b32 s10, v202, 48
	v_readlane_b32 s0, v202, 0
	v_readlane_b32 s9, v202, 32
	v_mov_b32_e32 v202, s8
	v_mov_b32_e32 v203, s10
	v_add_f32_e32 v202, s0, v202
	v_add_f32_e32 v203, s9, v203
	v_add_f32_e32 v202, v202, v203
	v_fmamk_f32 v200, v202, 0xbc800000, v200
	v_mul_f32_e32 v202, v200, v200
	s_nop 1
	v_mov_b32_dpp v202, v202 quad_perm:[1,0,3,2] row_mask:0xf bank_mask:0xf bound_ctrl:1
	v_fmac_f32_e32 v202, v200, v200
	s_nop 1
	v_add_f32_dpp v202, v202, v202 quad_perm:[2,3,0,1] row_mask:0xf bank_mask:0xf bound_ctrl:1
	s_nop 1
	v_add_f32_dpp v202, v202, v202 row_half_mirror row_mask:0xf bank_mask:0xf bound_ctrl:1
	s_nop 1
	v_add_f32_dpp v202, v202, v202 row_mirror row_mask:0xf bank_mask:0xf bound_ctrl:1
	s_nop 0
	v_readlane_b32 s8, v202, 16
	v_readlane_b32 s10, v202, 48
	v_readlane_b32 s0, v202, 0
	v_readlane_b32 s9, v202, 32
	v_mov_b32_e32 v202, s8
	v_mov_b32_e32 v203, s10
	v_add_f32_e32 v202, s0, v202
	v_add_f32_e32 v203, s9, v203
	v_add_f32_e32 v202, v202, v203
	v_fmamk_f32 v202, v202, 0x3c800000, v221
	v_rsq_f32_e32 v202, v202
	v_add_u32_e32 v207, 0x3000, v113
	v_mul_f32_e32 v200, v200, v202
	v_fma_f32 v200, v120, v200, v121
	s_waitcnt lgkmcnt(0)
	v_fmac_f32_e32 v200, v201, v204
	v_mul_f32_e32 v200, v205, v200
	v_bfe_u32 v203, v200, 16, 1
	v_add3_u32 v206, v200, v203, s33
	global_store_short_d16_hi v207, v206, s[70:71]
	ds_read2st64_b32 v[200:201], v109 offset0:56 offset1:61
	ds_read2st64_b32 v[204:205], v109 offset0:62 offset1:63
	s_waitcnt lgkmcnt(1)
	v_add_f32_dpp v202, v200, v200 quad_perm:[1,0,3,2] row_mask:0xf bank_mask:0xf bound_ctrl:1
	s_nop 1
	v_add_f32_dpp v202, v202, v202 quad_perm:[2,3,0,1] row_mask:0xf bank_mask:0xf bound_ctrl:1
	s_nop 1
	v_add_f32_dpp v202, v202, v202 row_half_mirror row_mask:0xf bank_mask:0xf bound_ctrl:1
	s_nop 1
	v_add_f32_dpp v202, v202, v202 row_mirror row_mask:0xf bank_mask:0xf bound_ctrl:1
	s_nop 0
	v_readlane_b32 s8, v202, 16
	v_readlane_b32 s10, v202, 48
	v_readlane_b32 s0, v202, 0
	v_readlane_b32 s9, v202, 32
	v_mov_b32_e32 v202, s8
	v_mov_b32_e32 v203, s10
	v_add_f32_e32 v202, s0, v202
	v_add_f32_e32 v203, s9, v203
	v_add_f32_e32 v202, v202, v203
	v_fmamk_f32 v200, v202, 0xbc800000, v200
	v_mul_f32_e32 v202, v200, v200
	s_nop 1
	v_mov_b32_dpp v202, v202 quad_perm:[1,0,3,2] row_mask:0xf bank_mask:0xf bound_ctrl:1
	v_fmac_f32_e32 v202, v200, v200
	s_nop 1
	v_add_f32_dpp v202, v202, v202 quad_perm:[2,3,0,1] row_mask:0xf bank_mask:0xf bound_ctrl:1
	s_nop 1
	v_add_f32_dpp v202, v202, v202 row_half_mirror row_mask:0xf bank_mask:0xf bound_ctrl:1
	s_nop 1
	v_add_f32_dpp v202, v202, v202 row_mirror row_mask:0xf bank_mask:0xf bound_ctrl:1
	s_nop 0
	v_readlane_b32 s8, v202, 16
	v_readlane_b32 s10, v202, 48
	v_readlane_b32 s0, v202, 0
	v_readlane_b32 s9, v202, 32
	v_mov_b32_e32 v202, s8
	v_mov_b32_e32 v203, s10
	v_add_f32_e32 v202, s0, v202
	v_add_f32_e32 v203, s9, v203
	v_add_f32_e32 v202, v202, v203
	v_fmamk_f32 v202, v202, 0x3c800000, v221
	v_rsq_f32_e32 v202, v202
	v_add_u32_e32 v207, 0x3800, v113
	v_mul_f32_e32 v200, v200, v202
	v_fma_f32 v200, v120, v200, v121
	s_waitcnt lgkmcnt(0)
	v_fmac_f32_e32 v200, v201, v204
	v_mul_f32_e32 v200, v205, v200
	v_bfe_u32 v203, v200, 16, 1
	v_add3_u32 v206, v200, v203, s33
	global_store_short_d16_hi v207, v206, s[70:71]
	v_add_u32_e32 v113, 0x4000, v113
	s_add_i32 s1, s1, 1
	s_cmp_eq_u32 s1, 8
	s_cbranch_scc0 .Lm1_sub
	s_add_i32 s2, s2, s58
	s_cmpk_gt_i32 s2, 0x7ff
	s_cbranch_scc0 .LBB0_205
	s_load_dwordx2 s[72:73], s[30:31], 0x118
	v_readlane_b32 s12, v253, 17
	v_readlane_b32 s13, v253, 18
	v_readlane_b32 s67, v255, 14
	v_readlane_b32 s71, v255, 15
	v_readlane_b32 s51, v255, 16
